# MLA: static s_setprio 1 for waves 4-7 during the tile loop (reset at the unit epilogue)
# speedup vs baseline: 1.0005x; 1.0005x over previous
; __device__ __forceinline__ unsigned pk_bf16(float lo, float hi) { typedef float f2_t __attribute__((ext_vector_type(2))); typedef __bf16 b2_t __attribute__((ext_vector_type(2))); f2_t v = {lo, hi}; b2_t b = __builtin_convertvector(v, b2_t); return __builtin_bit_cast(unsigned, b); }
; __device__ __forceinline__ float xhalf_sum(float x) { float a, b; xhalf_swap(x, a, b); return a + b; }
; __device__ __forceinline__ void swap32u(unsigned& a, unsigned& b) { asm volatile("s_nop 1\n\tv_permlane32_swap_b32 %0, %1\n\ts_nop 1" : "+v"(a), "+v"(b)); }
; __device__ __forceinline__ void store_ot(bf16_t* orow  , const f32x16& o, int d0, int hh, float inv) {
;     unsigned lo[4], hi[4];
; #pragma unroll
;     for (int g = 0; g < 4; ++g) { lo[g] = pk_bf16(o[4 * g] * inv, o[4 * g + 1] * inv); hi[g] = pk_bf16(o[4 * g + 2] * inv, o[4 * g + 3] * inv); }
; #pragma unroll
;     for (int k = 0; k < 4; k += 2) {
;         swap32u(lo[k], lo[k + 1]); swap32u(hi[k], hi[k + 1]);
;         u32x4 w; w.x = lo[k]; w.y = hi[k]; w.z = lo[k + 1]; w.w = hi[k + 1];
;         *(u32x4*)(orow + d0 + 8 * (k + hh)) = w;
;     }
; }
; __device__ __forceinline__ void mla_unit2(LAS unsigned char* lds, const bf16_t* QB, const bf16_t* KB, const bf16_t* VT, bf16_t* OB, int b, int h, int qb, int wv) {
;     ...
;     la = xhalf_sum(la); lb = xhalf_sum(lb);
;     const float ia = 1.0f / la, ib = 1.0f / lb;
;     bf16_t* orow = OB + (rowbase + q0 + r) * 512 + h * 64;
;     store_ot(orow, oa0, 0, hh, ia); store_ot(orow, oa1, 32, hh, ia);
;     store_ot(orow + (size_t)32 * 512, ob0, 0, hh, ib); store_ot(orow + (size_t)32 * 512, ob1, 32, hh, ib);
.LBB0_659:
	s_setprio 0
	v_mov_b32_e32 v0, v225
	s_nop 1
	v_permlane32_swap_b32 v225, v0
	s_nop 1
	v_mov_b32_e32 v2, v222
	v_add_f32_e32 v0, v225, v0
	v_div_scale_f32 v3, s[0:1], v0, v0, 1.0
	v_rcp_f32_e32 v4, v3
	s_nop 1
	v_permlane32_swap_b32 v222, v2
	s_nop 1
	v_mov_b32_e32 v194, v220
	v_add_f32_e32 v2, v222, v2
	v_fma_f32 v5, -v3, v4, 1.0
	v_fmac_f32_e32 v4, v5, v4
	v_div_scale_f32 v5, vcc, 1.0, v0, 1.0
	v_mul_f32_e32 v6, v5, v4
	v_fma_f32 v7, -v3, v6, v5
	v_fmac_f32_e32 v6, v7, v4
	v_fma_f32 v3, -v3, v6, v5
	v_div_fmas_f32 v3, v3, v4, v6
	v_div_fixup_f32 v10, v3, v0, 1.0
	v_div_scale_f32 v0, s[0:1], v2, v2, 1.0
	v_rcp_f32_e32 v3, v0
	v_pk_mul_f32 v[8:9], v[74:75], v[10:11] op_sel_hi:[1,0]
	s_mov_b64 s[0:1], 0x8000
	v_fma_f32 v4, -v0, v3, 1.0
	v_fmac_f32_e32 v3, v4, v3
	v_div_scale_f32 v4, vcc, 1.0, v2, 1.0
	v_mul_f32_e32 v5, v4, v3
	v_fma_f32 v6, -v0, v5, v4
	v_fmac_f32_e32 v5, v6, v3
	v_fma_f32 v0, -v0, v5, v4
	v_div_fmas_f32 v0, v0, v3, v5
	v_div_fixup_f32 v12, v0, v2, 1.0
	v_lshlrev_b64 v[2:3], 10, v[198:199]
	v_lshl_add_u64 v[14:15], s[28:29], 0, v[2:3]
	v_pk_mul_f32 v[2:3], v[64:65], v[10:11] op_sel_hi:[1,0]
	v_pk_mul_f32 v[4:5], v[66:67], v[10:11] op_sel_hi:[1,0]
	v_cvt_pk_bf16_f32 v2, v2, v3
	v_cvt_pk_bf16_f32 v3, v4, v5
	v_pk_mul_f32 v[4:5], v[68:69], v[10:11] op_sel_hi:[1,0]
	v_pk_mul_f32 v[6:7], v[70:71], v[10:11] op_sel_hi:[1,0]
	v_cvt_pk_bf16_f32 v4, v4, v5
	v_cvt_pk_bf16_f32 v5, v6, v7
	v_pk_mul_f32 v[6:7], v[72:73], v[10:11] op_sel_hi:[1,0]
	v_pk_mul_f32 v[64:65], v[78:79], v[10:11] op_sel_hi:[1,0]
	v_cvt_pk_bf16_f32 v6, v6, v7
	v_cvt_pk_bf16_f32 v7, v8, v9
	v_pk_mul_f32 v[8:9], v[76:77], v[10:11] op_sel_hi:[1,0]
	v_lshlrev_b32_e32 v0, 1, v196
	v_cvt_pk_bf16_f32 v8, v8, v9
	v_cvt_pk_bf16_f32 v9, v64, v65
	s_nop 1
	v_permlane32_swap_b32 v2, v4
	s_nop 1
	s_nop 1
	v_permlane32_swap_b32 v3, v5
	s_nop 1
	v_lshl_add_u64 v[14:15], v[14:15], 0, v[0:1]
	global_store_dwordx4 v[14:15], v[2:5], off
	s_nop 1
	v_permlane32_swap_b32 v6, v8
	s_nop 1
	s_nop 1
	v_permlane32_swap_b32 v7, v9
	s_nop 1
	global_store_dwordx4 v[14:15], v[6:9], off offset:32
	s_nop 0
	v_pk_mul_f32 v[2:3], v[48:49], v[10:11] op_sel_hi:[1,0]
	v_pk_mul_f32 v[4:5], v[50:51], v[10:11] op_sel_hi:[1,0]
	v_cvt_pk_bf16_f32 v2, v2, v3
	v_cvt_pk_bf16_f32 v3, v4, v5
	v_pk_mul_f32 v[4:5], v[52:53], v[10:11] op_sel_hi:[1,0]
	v_pk_mul_f32 v[6:7], v[54:55], v[10:11] op_sel_hi:[1,0]
	v_cvt_pk_bf16_f32 v4, v4, v5
	v_cvt_pk_bf16_f32 v5, v6, v7
	v_pk_mul_f32 v[6:7], v[56:57], v[10:11] op_sel_hi:[1,0]
	v_pk_mul_f32 v[8:9], v[58:59], v[10:11] op_sel_hi:[1,0]
	v_cvt_pk_bf16_f32 v6, v6, v7
	v_cvt_pk_bf16_f32 v7, v8, v9
	v_pk_mul_f32 v[8:9], v[60:61], v[10:11] op_sel_hi:[1,0]
	v_pk_mul_f32 v[10:11], v[62:63], v[10:11] op_sel_hi:[1,0]
	v_cvt_pk_bf16_f32 v8, v8, v9
	v_cvt_pk_bf16_f32 v9, v10, v11
	s_nop 1
	v_permlane32_swap_b32 v2, v4
	s_nop 1
	s_nop 1
	v_permlane32_swap_b32 v3, v5
	s_nop 1
	global_store_dwordx4 v[14:15], v[2:5], off offset:64
	s_nop 1
	v_permlane32_swap_b32 v6, v8
	s_nop 1
	s_nop 1
	v_permlane32_swap_b32 v7, v9
	s_nop 1
	global_store_dwordx4 v[14:15], v[6:9], off offset:96
	v_pk_mul_f32 v[10:11], v[46:47], v[12:13] op_sel_hi:[1,0]
	v_pk_mul_f32 v[2:3], v[32:33], v[12:13] op_sel_hi:[1,0]
	v_pk_mul_f32 v[4:5], v[34:35], v[12:13] op_sel_hi:[1,0]
	v_cvt_pk_bf16_f32 v2, v2, v3
	v_cvt_pk_bf16_f32 v3, v4, v5
	v_pk_mul_f32 v[4:5], v[36:37], v[12:13] op_sel_hi:[1,0]
	v_pk_mul_f32 v[6:7], v[38:39], v[12:13] op_sel_hi:[1,0]
	v_cvt_pk_bf16_f32 v4, v4, v5
	v_cvt_pk_bf16_f32 v5, v6, v7
	v_pk_mul_f32 v[6:7], v[40:41], v[12:13] op_sel_hi:[1,0]
	v_pk_mul_f32 v[8:9], v[42:43], v[12:13] op_sel_hi:[1,0]
	v_cvt_pk_bf16_f32 v6, v6, v7
	v_cvt_pk_bf16_f32 v7, v8, v9
	v_pk_mul_f32 v[8:9], v[44:45], v[12:13] op_sel_hi:[1,0]
	s_nop 1
	v_permlane32_swap_b32 v2, v4
	s_nop 1
	s_nop 1
	v_permlane32_swap_b32 v3, v5
	s_nop 1
	s_nop 0
	v_cvt_pk_bf16_f32 v8, v8, v9
	v_cvt_pk_bf16_f32 v9, v10, v11
	v_lshl_add_u64 v[10:11], v[14:15], 0, s[0:1]
	s_mov_b32 s0, 0x8000
	v_add_co_u32_e32 v32, vcc, s0, v14
	s_mov_b64 s[0:1], 0x8040
	s_nop 0
	v_addc_co_u32_e32 v33, vcc, 0, v15, vcc
	global_store_dwordx4 v[32:33], v[2:5], off
	s_nop 1
	v_permlane32_swap_b32 v6, v8
	s_nop 1
	s_nop 1
	v_permlane32_swap_b32 v7, v9
	s_nop 1
	global_store_dwordx4 v[10:11], v[6:9], off offset:32
	v_pk_mul_f32 v[10:11], v[30:31], v[12:13] op_sel_hi:[1,0]
	v_pk_mul_f32 v[2:3], v[16:17], v[12:13] op_sel_hi:[1,0]
	v_pk_mul_f32 v[4:5], v[18:19], v[12:13] op_sel_hi:[1,0]
	v_cvt_pk_bf16_f32 v2, v2, v3
	v_cvt_pk_bf16_f32 v3, v4, v5
	v_pk_mul_f32 v[4:5], v[20:21], v[12:13] op_sel_hi:[1,0]
	v_pk_mul_f32 v[6:7], v[22:23], v[12:13] op_sel_hi:[1,0]
	v_cvt_pk_bf16_f32 v4, v4, v5
	v_cvt_pk_bf16_f32 v5, v6, v7
	v_pk_mul_f32 v[6:7], v[24:25], v[12:13] op_sel_hi:[1,0]
	v_pk_mul_f32 v[8:9], v[26:27], v[12:13] op_sel_hi:[1,0]
	v_cvt_pk_bf16_f32 v6, v6, v7
	v_cvt_pk_bf16_f32 v7, v8, v9
	v_pk_mul_f32 v[8:9], v[28:29], v[12:13] op_sel_hi:[1,0]
	s_and_b64 vcc, exec, s[30:31]
	v_cvt_pk_bf16_f32 v8, v8, v9
	v_cvt_pk_bf16_f32 v9, v10, v11
	v_lshl_add_u64 v[10:11], v[14:15], 0, s[0:1]
	s_mov_b64 s[0:1], 0
	s_nop 1
	v_permlane32_swap_b32 v2, v4
	s_nop 1
	s_nop 1
	v_permlane32_swap_b32 v3, v5
	s_nop 1
	global_store_dwordx4 v[32:33], v[2:5], off offset:64
	s_nop 1
	v_permlane32_swap_b32 v6, v8
	s_nop 1
	s_nop 1
	v_permlane32_swap_b32 v7, v9
	s_nop 1
	global_store_dwordx4 v[10:11], v[6:9], off offset:32
	s_cbranch_vccnz .LBB0_653
; __device__ __forceinline__ int hw_lane_id() { return (int)__builtin_amdgcn_mbcnt_hi(~0u, __builtin_amdgcn_mbcnt_lo(~0u, 0u)); }
; #define LAS __attribute__((address_space(3)))
; __device__ __forceinline__ void mla_unit2(LAS unsigned char* lds, const bf16_t* QB, const bf16_t* KB, const bf16_t* VT, bf16_t* OB, int b, int h, int qb, int wv) {
;     int tid_ = wv * 64 + hw_lane_id(); asm volatile("" : "+v"(tid_));
;     const int tid = tid_, lane = tid & 63, wid = __builtin_amdgcn_readfirstlane(tid >> 6), r = lane & 31, hh = lane >> 5;
;     const int q0 = qb * 512 + wid * 64;
;     const size_t rowbase = (size_t)b * SEQ;
;     bf16x8 qa[6], qbf[6];
;     { const bf16_t* qp = QB + (rowbase + q0 + r) * NQB + h * 96 + 8 * hh;
; #pragma unroll
;       for (int s = 0; s < 6; ++s) { qa[s] = *(const bf16x8*)(qp + 16 * s); qbf[s] = *(const bf16x8*)(qp + (size_t)32 * NQB + 16 * s); } }
;     f32x16 oa0, oa1, ob0, ob1;
; #pragma unroll
;     for (int i = 0; i < 16; ++i) { oa0[i] = 0.f; oa1[i] = 0.f; ob0[i] = 0.f; ob1[i] = 0.f; }
;     float ma = -INFINITY, mb = -INFINITY, la = 0.f, lb = 0.f;
;     const int ntiles = 8 * (qb + 1), nact = q0 / 64 + 1, tl = ntiles - 1;
;     const int kA_key = tid / 12, kA_part = tid % 12, kC_key = (512 + (tid & 255)) / 12, kC_part = (512 + (tid & 255)) % 12, v_d = tid >> 3, v_part = tid & 7;
;     const bf16_t* gKA = KB + (rowbase + kA_key) * NQB + h * 96 + kA_part * 8;
;     const bf16_t* gKC = KB + (rowbase + kC_key) * NQB + h * 96 + kC_part * 8;
;     const bf16_t* gV = VT + ((size_t)(b * 8 + h) * 64 + v_d) * SEQ + v_part * 8;
;     const int lKA = kA_key * MK_ROW + kA_part * 16, lKC = kC_key * MK_ROW + kC_part * 16, lV = MK_BYTES + v_d * MV_ROW + v_part * 16;
;     u32x4 ra = *(const u32x4*)gKA, rc = *(const u32x4*)gKC, rv = *(const u32x4*)gV;
;     __syncthreads();
;     *(LAS u32x4*)(lds + lKA) = ra; *(LAS u32x4*)(lds + lKC) = rc; *(LAS u32x4*)(lds + lV) = rv;
;     __syncthreads();
.LBB0_660:
	v_mov_b32_e32 v20, v194
	s_mov_b32 s12, 0x2aaaaaab
	s_xor_b64 s[30:31], s[0:1], -1
	v_mul_hi_i32 v0, v20, s12
	v_lshrrev_b32_e32 v2, 31, v0
	v_ashrrev_i32_e32 v0, 1, v0
	v_add_u32_e32 v14, v0, v2
	v_mul_lo_u32 v0, v14, 12
	v_sub_u32_e32 v24, v20, v0
	v_mov_b32_e32 v0, 0xff
	s_movk_i32 s12, 0x200
	v_bitop3_b16 v0, v20, s12, v0 bitop3:0xec
	s_mov_b32 s12, 0xaaab
	v_mul_u32_u24_sdwa v2, v0, s12 dst_sel:DWORD dst_unused:UNUSED_PAD src0_sel:WORD_0 src1_sel:DWORD
	v_lshrrev_b32_e32 v25, 19, v2
	v_mul_lo_u16_e32 v2, 12, v25
	v_ashrrev_i32_e32 v15, 31, v14
	v_sub_u16_e32 v0, v0, v2
	v_lshl_add_u64 v[2:3], s[4:5], 0, v[14:15]
	v_mov_b64_e32 v[4:5], s[8:9]
	s_and_b64 s[0:1], s[0:1], exec
	v_mad_u64_u32 v[6:7], s[16:17], v2, s33, v[4:5]
	v_lshlrev_b32_e32 v2, 3, v24
	s_cselect_b32 s12, s69, s68
	v_readfirstlane_b32 s0, v20
	v_mad_i32_i24 v7, v3, s33, v7
	v_ashrrev_i32_e32 v3, 31, v2
	s_lshl_b32 s75, s12, 9
	s_and_b32 s70, s0, 0xffffffc0
	v_lshl_add_u64 v[200:201], v[2:3], 1, v[6:7]
	v_or_b32_e32 v2, s4, v25
	s_add_i32 s70, s70, s75
	v_ashrrev_i32_e32 v16, 3, v20
	v_mad_u64_u32 v[2:3], s[16:17], v2, s33, v[4:5]
	v_mov_b32_e32 v22, 0x600
	s_ashr_i32 s0, s70, 31
	v_mad_i32_i24 v3, s5, v22, v3
	v_lshlrev_b32_e32 v0, 4, v0
	v_ashrrev_i32_e32 v17, 31, v16
	v_and_b32_e32 v15, 31, v20
	s_add_u32 s1, s4, s70
	v_lshl_add_u64 v[202:203], v[2:3], 0, v[0:1]
	v_lshlrev_b64 v[2:3], 14, v[16:17]
	v_lshlrev_b32_e32 v12, 4, v20
	v_bfe_u32 v17, v20, 5, 1
	v_or_b32_e32 v198, s1, v15
	v_mov_b64_e32 v[20:21], s[6:7]
	s_addc_u32 s16, s5, s0
	v_mad_u64_u32 v[20:21], s[0:1], v198, s33, v[20:21]
	v_mad_i32_i24 v21, s16, v22, v21
	v_lshlrev_b32_e32 v206, 4, v17
	v_mov_b32_e32 v207, v1
	v_lshl_add_u64 v[10:11], s[10:11], 0, v[2:3]
	v_and_b32_e32 v18, 0x70, v12
	v_mov_b32_e32 v19, v1
	v_lshl_add_u64 v[20:21], v[20:21], 0, v[206:207]
	s_mov_b32 s0, 0xc000
	v_lshl_add_u64 v[204:205], v[10:11], 0, v[18:19]
	v_add_co_u32_e32 v22, vcc, s0, v20
	global_load_dwordx4 v[2:5], v[200:201], off
	global_load_dwordx4 v[6:9], v[202:203], off
	global_load_dwordx4 v[10:13], v[204:205], off
	global_load_dwordx4 v[144:147], v[20:21], off
	v_addc_co_u32_e32 v23, vcc, 0, v21, vcc
	global_load_dwordx4 v[148:151], v[20:21], off offset:32
	global_load_dwordx4 v[152:155], v[20:21], off offset:64
	global_load_dwordx4 v[156:159], v[22:23], off offset:32
	global_load_dwordx4 v[160:163], v[22:23], off offset:64
	global_load_dwordx4 v[164:167], v[20:21], off offset:96
	global_load_dwordx4 v[168:171], v[20:21], off offset:128
	global_load_dwordx4 v[172:175], v[22:23], off offset:96
	global_load_dwordx4 v[176:179], v[22:23], off offset:128
	global_load_dwordx4 v[180:183], v[22:23], off
	global_load_dwordx4 v[184:187], v[20:21], off offset:160
	global_load_dwordx4 v[188:191], v[22:23], off offset:160
	s_movk_i32 s0, 0xd0
	v_mul_lo_u32 v14, v14, s0
	v_mul_lo_u16_e32 v19, 0xd0, v25
	s_lshl_b32 s0, s12, 3
	v_lshl_add_u32 v197, v24, 4, v14
	v_add_u32_e32 v207, v0, v19
	s_or_b32 s73, s0, 7
	v_add_u32_e32 v0, 0, v197
	v_add_u32_e32 v14, 0, v207
	v_mad_u64_u32 v[208:209], s[0:1], v16, s19, v[18:19]
	s_or_b32 s74, s70, 32
	s_waitcnt vmcnt(63) expcnt(7) lgkmcnt(15)
	s_barrier
	v_mul_u32_u24_e32 v209, 0xd0, v15
	v_or_b32_e32 v211, s70, v15
	v_mul_u32_u24_e32 v213, 0x90, v15
	v_or_b32_e32 v214, s74, v15
	v_mov_b32_e32 v15, v1
	v_lshlrev_b32_e32 v196, 3, v17
	v_lshlrev_b32_e32 v212, 2, v17
	s_mov_b32 s71, 0
	s_mov_b32 s100, 1
	s_ashr_i32 s72, s70, 6
	v_mov_b32_e32 v199, s16
	s_addk_i32 s75, 0x200
	v_mov_b32_e32 v223, 0
	s_waitcnt vmcnt(14)
	ds_write_b128 v0, v[2:5]
	s_waitcnt vmcnt(13)
	ds_write_b128 v14, v[6:9]
	v_add_u32_e32 v0, 0, v208
	v_mov_b32_e32 v14, v1
	s_waitcnt vmcnt(12)
	ds_write_b128 v0, v[10:13] offset:13312
	v_mov_b32_e32 v0, v1
	v_mov_b32_e32 v2, v1
	v_mov_b32_e32 v3, v1
	v_mov_b32_e32 v4, v1
	v_mov_b32_e32 v5, v1
	v_mov_b32_e32 v6, v1
	v_mov_b32_e32 v7, v1
	v_mov_b32_e32 v8, v1
	v_mov_b32_e32 v9, v1
	v_mov_b32_e32 v10, v1
	v_mov_b32_e32 v11, v1
	v_mov_b32_e32 v12, v1
	v_mov_b32_e32 v13, v1
	v_mov_b64_e32 v[30:31], v[14:15]
	v_mov_b64_e32 v[46:47], v[14:15]
	v_mov_b64_e32 v[62:63], v[14:15]
	v_mov_b64_e32 v[78:79], v[14:15]
	v_mov_b32_e32 v222, 0
	s_mov_b32 s0, 0
	v_mov_b32_e32 v225, 0
	v_mov_b32_e32 v224, 0
	v_mov_b64_e32 v[28:29], v[12:13]
	v_mov_b64_e32 v[26:27], v[10:11]
	v_mov_b64_e32 v[24:25], v[8:9]
	v_mov_b64_e32 v[22:23], v[6:7]
	v_mov_b64_e32 v[20:21], v[4:5]
	v_mov_b64_e32 v[18:19], v[2:3]
	v_mov_b64_e32 v[16:17], v[0:1]
	v_mov_b64_e32 v[44:45], v[12:13]
	v_mov_b64_e32 v[42:43], v[10:11]
	v_mov_b64_e32 v[40:41], v[8:9]
	v_mov_b64_e32 v[38:39], v[6:7]
	v_mov_b64_e32 v[36:37], v[4:5]
	v_mov_b64_e32 v[34:35], v[2:3]
	v_mov_b64_e32 v[32:33], v[0:1]
	v_mov_b64_e32 v[60:61], v[12:13]
	v_mov_b64_e32 v[58:59], v[10:11]
	v_mov_b64_e32 v[56:57], v[8:9]
	v_mov_b64_e32 v[54:55], v[6:7]
	v_mov_b64_e32 v[52:53], v[4:5]
	v_mov_b64_e32 v[50:51], v[2:3]
	v_mov_b64_e32 v[48:49], v[0:1]
	v_mov_b64_e32 v[76:77], v[12:13]
	v_mov_b64_e32 v[74:75], v[10:11]
	v_mov_b64_e32 v[72:73], v[8:9]
	v_mov_b64_e32 v[70:71], v[6:7]
	v_mov_b64_e32 v[68:69], v[4:5]
	v_mov_b64_e32 v[66:67], v[2:3]
	v_mov_b64_e32 v[64:65], v[0:1]
	s_waitcnt lgkmcnt(0)
	s_barrier
	s_bitcmp1_b32 s72, 2
	s_cbranch_scc0 .Lmla_noprio
	s_setprio 1
; #define LAS __attribute__((address_space(3)))
; #define MFMA32(a, b, c) __builtin_amdgcn_mfma_f32_32x32x16_bf16((a), (b), (c), 0, 0, 0)
; __device__ __forceinline__ int crow(int i, int hh) { return (i & 3) + 8 * (i >> 2) + 4 * hh; }
; __device__ __forceinline__ void mla_softmax(f32x16& s0, f32x16& s1, f32x16& o0, f32x16& o1, float& m, float& l, int k0, int qrow0, int r, int hh) {
;     if (k0 + 63 > qrow0) {
;         const int qpos = qrow0 + r;
; #pragma unroll
;         for (int i = 0; i < 16; ++i) { const int kp = k0 + crow(i, hh); if (kp > qpos) s0[i] = -INFINITY; if (kp + 32 > qpos) s1[i] = -INFINITY; }
; __device__ __forceinline__ void mla_unit2(LAS unsigned char* lds, const bf16_t* QB, const bf16_t* KB, const bf16_t* VT, bf16_t* OB, int b, int h, int qb, int wv) {
;     ...
;     for (int t = 0; t < ntiles; ++t) {
;         LAS unsigned char* cur = lds + (t & 1) * M2BUF;
;         { const int tn = (t + 1 < tl) ? t + 1 : tl;
;           ra = *(const u32x4*)(gKA + (size_t)tn * 64 * NQB); rc = *(const u32x4*)(gKC + (size_t)tn * 64 * NQB); rv = *(const u32x4*)(gV + tn * 64); }
;         if (t < nact) {
;             const int k0 = t * 64;
;             f32x16 sa0, sa1, sb0, sb1;
;             { const LAS unsigned char* kp = cur + r * MK_ROW + hh * 16;
; #pragma unroll
;               for (int i = 0; i < 16; ++i) { sa0[i] = 0.f; sa1[i] = 0.f; sb0[i] = 0.f; sb1[i] = 0.f; }
; #pragma unroll
;               for (int hf = 0; hf < 2; ++hf) {
;                   bf16x8 ka[3], kc[3];
; #pragma unroll
;                   for (int s = 0; s < 3; ++s) { ka[s] = *(const LAS bf16x8*)(kp + (3 * hf + s) * 32); kc[s] = *(const LAS bf16x8*)(kp + 32 * MK_ROW + (3 * hf + s) * 32); }
;                   __builtin_amdgcn_sched_barrier(0);
; #pragma unroll
;                   for (int s = 0; s < 3; ++s) { sa0 = MFMA32(ka[s], qa[3 * hf + s], sa0); sa1 = MFMA32(kc[s], qa[3 * hf + s], sa1); sb0 = MFMA32(ka[s], qbf[3 * hf + s], sb0); sb1 = MFMA32(kc[s], qbf[3 * hf + s], sb1); }
;                   __builtin_amdgcn_sched_barrier(0);
;               } }
.Lmla_noprio:
.LBB0_661:
	s_add_i32 s76, s0, 1
	s_min_u32 s1, s76, s73
	s_mul_i32 s12, s1, 0x18000
	v_lshl_add_u64 v[2:3], v[200:201], 0, s[12:13]
	v_lshl_add_u64 v[4:5], v[202:203], 0, s[12:13]
	s_lshl_b32 s12, s1, 7
	v_lshl_add_u64 v[10:11], v[204:205], 0, s[12:13]
	global_load_dwordx4 v[6:9], v[2:3], off
	s_nop 0
	global_load_dwordx4 v[2:5], v[4:5], off
	s_cmp_gt_i32 s0, s72
	global_load_dwordx4 v[10:13], v[10:11], off
	s_cbranch_scc1 .LBB0_676
	s_bitcmp1_b32 s0, 0
	s_cselect_b32 s0, 0x5800, 0
	s_add_i32 s12, s0, 0
	v_add3_u32 v0, s12, v209, v206
	ds_read_b128 v[80:83], v0
	ds_read_b128 v[226:229], v0 offset:32
	ds_read_b128 v[84:87], v0 offset:6656
	ds_read_b128 v[230:233], v0 offset:64
	ds_read_b128 v[234:237], v0 offset:6688
	ds_read_b128 v[238:241], v0 offset:6720
	s_waitcnt vmcnt(14) lgkmcnt(5)
	v_mfma_f32_32x32x16_bf16 v[128:143], v[80:83], v[144:147], 0
	s_waitcnt lgkmcnt(3)
	v_mfma_f32_32x32x16_bf16 v[112:127], v[84:87], v[144:147], 0
	s_waitcnt vmcnt(5)
	v_mfma_f32_32x32x16_bf16 v[96:111], v[80:83], v[180:183], 0
	v_mfma_f32_32x32x16_bf16 v[80:95], v[84:87], v[180:183], 0
	v_mfma_f32_32x32x16_bf16 v[128:143], v[226:229], v[148:151], v[128:143]
	s_waitcnt lgkmcnt(1)
	v_mfma_f32_32x32x16_bf16 v[112:127], v[234:237], v[148:151], v[112:127]
	v_mfma_f32_32x32x16_bf16 v[96:111], v[226:229], v[156:159], v[96:111]
	v_mfma_f32_32x32x16_bf16 v[80:95], v[234:237], v[156:159], v[80:95]
	v_mfma_f32_32x32x16_bf16 v[128:143], v[230:233], v[152:155], v[128:143]
	s_waitcnt lgkmcnt(0)
	v_mfma_f32_32x32x16_bf16 v[112:127], v[238:241], v[152:155], v[112:127]
	v_mfma_f32_32x32x16_bf16 v[96:111], v[230:233], v[160:163], v[96:111]
	v_mfma_f32_32x32x16_bf16 v[80:95], v[238:241], v[160:163], v[80:95]
	ds_read_b128 v[226:229], v0 offset:96
	ds_read_b128 v[230:233], v0 offset:128
	ds_read_b128 v[234:237], v0 offset:6752
	ds_read_b128 v[238:241], v0 offset:160
	ds_read_b128 v[242:245], v0 offset:6784
	ds_read_b128 v[246:249], v0 offset:6816
	s_waitcnt lgkmcnt(5)
	v_mfma_f32_32x32x16_bf16 v[128:143], v[226:229], v[164:167], v[128:143]
	s_waitcnt lgkmcnt(3)
	v_mfma_f32_32x32x16_bf16 v[112:127], v[234:237], v[164:167], v[112:127]
	v_mfma_f32_32x32x16_bf16 v[96:111], v[226:229], v[172:175], v[96:111]
	v_mfma_f32_32x32x16_bf16 v[80:95], v[234:237], v[172:175], v[80:95]
	v_mfma_f32_32x32x16_bf16 v[128:143], v[230:233], v[168:171], v[128:143]
	s_waitcnt lgkmcnt(1)
	v_mfma_f32_32x32x16_bf16 v[112:127], v[242:245], v[168:171], v[112:127]
	v_mfma_f32_32x32x16_bf16 v[96:111], v[230:233], v[176:179], v[96:111]
	v_mfma_f32_32x32x16_bf16 v[80:95], v[242:245], v[176:179], v[80:95]
	s_waitcnt vmcnt(4)
	v_mfma_f32_32x32x16_bf16 v[128:143], v[238:241], v[184:187], v[128:143]
	s_waitcnt lgkmcnt(0)
	v_mfma_f32_32x32x16_bf16 v[112:127], v[246:249], v[184:187], v[112:127]
	s_waitcnt vmcnt(3)
	v_mfma_f32_32x32x16_bf16 v[96:111], v[238:241], v[188:191], v[96:111]
	v_mfma_f32_32x32x16_bf16 v[80:95], v[246:249], v[188:191], v[80:95]
	s_add_i32 s25, s71, 63
	s_cmp_le_i32 s25, s70
	s_nop 7
	s_cbranch_scc1 .Lmla_nomask
	s_cmp_eq_u32 s100, 0
	s_cbranch_scc1 .Lmla_m663
	s_mov_b32 s100, 0
	s_cmp_lg_u32 s71, 0
	s_cbranch_scc1 .Lmla_m663
	v_mov_b32_e32 v224, 0xff800000
	v_mov_b32_e32 v223, 0xff800000
